# mixer-A far part, peeled first iteration: serialized bias-table reads batched into one burst (counted LDS waits widened, MFMA-to-VALU spacing re-padded)
# speedup vs baseline: 1.0040x; 1.0003x over previous
; template <int MODE, int NQ, int TS, bool FAST = false> ...
;     ...
;       m2[nq] = (MODE == 2) ? sink2 : -1e30f; l[nq] = 0.f;
; #pragma unroll
;       for (int r = 0; r < 16; ++r) { o[nq][0][r] = 0.f; o[nq][1][r] = 0.f; }
;     }
;   }
;   PG8_LAS unsigned char* L = (PG8_LAS unsigned char*)lds;
;   const int kkey_ = wave * 8 + (lane >> 3);
;   const bf16_t* kg = proj + (size_t)(seq_base + TS * kkey_) * ld + koff + (((lane & 7) ^ ((kkey_ >> 1) & 7)) * 8);
;   const bf16_t* vg = proj + (size_t)(seq_base + TS * ((wave & 3) * 16 + (lane >> 2))) * ld + voff + ((wave >> 2) * 4 + (lane & 3)) * 8;
;   const unsigned sdst = (unsigned)__builtin_amdgcn_readfirstlane(wave * 1024);
;     ...
;   const int ktl = kt1 - 1;
;   constexpr int TAB_OFF = 6 * 16384, TAB_N = (MODE == 3) ? 640 : 1024, TAB_ZERO = TAB_N / 2;
;   if (MODE == 0 || MODE == 3) {
;     float* tab = (float*)(lds + TAB_OFF);
;     for (int e = tid; e < TAB_N; e += 512) {
;       const int oo = e - TAB_ZERO, aa = oo < 0 ? -oo : oo;
;       if (MODE == 0) {
;         const int c = (aa <= 64 ? 1 : 0) + (((oo & 3) == 0 && aa <= 256) ? 1 : 0) + (((oo & 15) == 0 && aa <= 256) ? 1 : 0);
;         tab[e] = c ? (-slope2 * (float)aa + (c == 1 ? 0.f : (c == 2 ? 1.f : 1.5849625007f))) : -1e30f;
;       } else {
;         tab[e] = (aa >= 17 && aa <= 64) ? -slope2 * (float)(16 * aa) : -1e30f;
;       }
;     }
;   }
;   if (MODE == 2) {
;     float* tab = (float*)(lds + TAB_OFF) + (wave & 3) * 512;
; #pragma unroll
;     for (int i = 0; i < 4; ++i) { const int e = (wave >> 2) * 64 + lane + 128 * i; const int oo = e - 256, aa = oo < 0 ? -oo : oo; tab[e] = (aa <= 128) ? -slope2 * (float)aa : -1e30f; }
;   }
;   ATT_ISSUE(kt0, 0); ATT_ISSUE((kt0 + 1 < ktl ? kt0 + 1 : ktl), 1); ATT_ISSUE((kt0 + 2 < ktl ? kt0 + 2 : ktl), 2); ATT_ISSUE((kt0 + 3 < ktl ? kt0 + 3 : ktl), 3);
;   asm volatile("s_waitcnt vmcnt(6) lgkmcnt(0)\n\ts_barrier" ::: "memory");
;   int kfo4[4];
; #pragma unroll
;   for (int ks = 0; ks < 4; ++ks) kfo4[ks] = r32 * 128 + (((2 * ks + hh) ^ ((r32 >> 1) & 7)) << 4);
;   const int vfo = 8192 + (4 * hh + ((lane & 15) >> 2)) * 64 + ((lane >> 4) & 1) * 32 + (lane & 3) * 8;
;   const bool g2 = wave >= 4;
;     ...
;   for (int kt = kt0; kt < kt1; ++kt) {
;     { const int tn = (kt + 4 < ktl) ? kt + 4 : ktl; int s4 = slot + 4; if (s4 >= NS) s4 -= NS; ATT_ISSUE(tn, s4); }
;     const bool act = tile_active(kt);
;     if (!g2) {
.LBB0_266:
	s_or_b64 exec, exec, s[28:29]
	s_sub_i32 s0, s7, 64
	v_and_b32_e32 v103, 63, v2
	s_ashr_i32 s14, s0, 6
	s_add_i32 s0, s7, 0x13f
	s_lshr_b32 s0, s0, 6
	v_lshrrev_b32_e32 v0, 3, v103
	s_max_i32 s8, s14, 0
	s_or_b32 s1, s0, 1
	v_lshl_or_b32 v0, v10, 3, v0
	s_cmp_lt_u32 s0, s6
	v_lshl_add_u32 v3, v0, 4, s5
	v_mov_b64_e32 v[4:5], s[66:67]
	v_lshrrev_b32_e32 v0, 1, v0
	s_cselect_b32 s15, s1, s6
	v_mad_i64_i32 v[4:5], s[0:1], v3, s24, v[4:5]
	v_xor_b32_e32 v0, v0, v2
	s_lshl_b64 s[0:1], s[40:41], 1
	v_lshlrev_b32_e32 v0, 4, v0
	v_lshl_add_u64 v[4:5], v[4:5], 0, s[0:1]
	v_and_b32_e32 v0, 0x70, v0
	v_lshl_add_u64 v[98:99], v[4:5], 0, v[0:1]
	v_lshlrev_b32_e32 v0, 4, v10
	v_lshrrev_b32_e32 v3, 2, v103
	v_and_or_b32 v0, v0, 48, v3
	v_lshl_add_u32 v0, v0, 4, s5
	s_movk_i32 s5, 0x900
	v_mul_lo_u32 v0, v0, s5
	v_lshl_add_u64 v[4:5], v[0:1], 1, s[66:67]
	v_lshl_add_u64 v[4:5], v[4:5], 0, s[0:1]
	v_and_b32_e32 v0, 3, v2
	s_mov_b32 s0, 0x1ffffffc
	v_and_or_b32 v3, v10, s0, v0
	v_lshlrev_b32_e32 v6, 3, v3
	v_ashrrev_i32_e32 v7, 31, v6
	v_lshl_add_u64 v[100:101], v[6:7], 1, v[4:5]
	s_lshl_b32 s16, s9, 10
	v_mad_u64_u32 v[4:5], s[0:1], s8, v235, v[98:99]
	v_lshl_add_u64 v[4:5], v[4:5], 0, s[60:61]
	s_mov_b32 m0, s16
	s_add_i32 s5, s15, -1
	global_load_lds_dwordx4 v[4:5], off
	v_mad_u64_u32 v[4:5], s[0:1], s8, v235, v[100:101]
	s_add_i32 s6, s8, 1
	v_lshl_add_u64 v[4:5], v[4:5], 0, s[58:59]
	s_add_i32 m0, s16, 0x2000
	s_min_u32 s7, s6, s5
	global_load_lds_dwordx4 v[4:5], off
	v_mad_u64_u32 v[4:5], s[0:1], s7, v235, v[98:99]
	v_lshl_add_u64 v[4:5], v[4:5], 0, s[60:61]
	s_add_i32 m0, s16, 0x4000
	v_lshlrev_b32_e32 v3, 4, v2
	global_load_lds_dwordx4 v[4:5], off
	v_mad_u64_u32 v[4:5], s[0:1], s7, v235, v[100:101]
	s_add_i32 s0, s8, 2
	v_lshl_add_u64 v[4:5], v[4:5], 0, s[58:59]
	s_add_i32 m0, s16, 0x6000
	s_min_u32 s7, s0, s5
	global_load_lds_dwordx4 v[4:5], off
	v_mad_u64_u32 v[4:5], s[0:1], s7, v235, v[98:99]
	v_lshl_add_u64 v[4:5], v[4:5], 0, s[60:61]
	s_add_i32 m0, s16, 0x8000
	v_and_b32_e32 v3, 0xc0, v3
	global_load_lds_dwordx4 v[4:5], off
	v_mad_u64_u32 v[4:5], s[0:1], s7, v235, v[100:101]
	s_add_i32 s0, s8, 3
	v_lshl_add_u64 v[4:5], v[4:5], 0, s[58:59]
	s_add_i32 m0, s16, 0xa000
	s_min_u32 s7, s0, s5
	global_load_lds_dwordx4 v[4:5], off
	v_mad_u64_u32 v[4:5], s[0:1], s7, v235, v[98:99]
	v_lshl_add_u64 v[4:5], v[4:5], 0, s[60:61]
	s_add_i32 m0, s16, 0xc000
	v_lshl_or_b32 v3, v105, 8, v3
	global_load_lds_dwordx4 v[4:5], off
	v_mad_u64_u32 v[4:5], s[0:1], s7, v235, v[100:101]
	v_lshl_add_u64 v[4:5], v[4:5], 0, s[58:59]
	s_add_i32 m0, s16, 0xe000
	v_lshlrev_b32_e32 v0, 3, v0
	global_load_lds_dwordx4 v[4:5], off
	s_waitcnt vmcnt(6) lgkmcnt(0)
	s_barrier
	v_lshlrev_b32_e32 v4, 1, v2
	v_and_b32_e32 v4, 32, v4
	s_mov_b32 s9, 0
	v_or3_b32 v106, v3, v4, v0
	v_cmp_lt_i32_e64 s[36:37], 3, v10
	v_cmp_gt_i32_e64 s[38:39], 4, v10
	s_cmp_lt_i32 s14, s15
	v_subrev_u32_e32 v107, 64, v9
	v_add_u32_e32 v108, 0x5f, v9
	s_cbranch_scc0 .LBB0_271
	s_add_i32 s0, s8, 4
	s_min_u32 s7, s0, s5
	v_mad_u64_u32 v[4:5], s[0:1], s7, v235, v[98:99]
	v_lshl_add_u64 v[4:5], v[4:5], 0, s[60:61]
	s_add_i32 m0, s16, 0x10000
	v_lshrrev_b32_e32 v0, 1, v2
	global_load_lds_dwordx4 v[4:5], off
	v_mad_u64_u32 v[4:5], s[0:1], s7, v235, v[100:101]
	v_lshl_add_u64 v[4:5], v[4:5], 0, s[58:59]
	s_add_i32 m0, s16, 0x12000
	v_bfe_u32 v2, v2, 1, 3
	global_load_lds_dwordx4 v[4:5], off
	s_lshl_b32 s7, s8, 6
	v_bitop3_b32 v3, v105, v2, 6 bitop3:0x36
	v_lshlrev_b32_e32 v4, 7, v8
	v_bitop3_b32 v0, v105, v0, 7 bitop3:0x78
	s_or_b32 s0, s7, 63
	v_lshl_or_b32 v97, v3, 4, v4
	v_bitop3_b32 v3, v105, v2, 4 bitop3:0x36
	v_bitop3_b32 v2, v105, v2, 2 bitop3:0x36
	v_lshl_or_b32 v111, v0, 4, v4
	v_lshlrev_b32_e32 v0, 2, v105
	v_cmp_ge_i32_e32 vcc, s0, v107
	v_cmp_le_i32_e64 s[0:1], s7, v108
	v_lshl_or_b32 v109, v3, 4, v4
	v_lshl_or_b32 v110, v2, 4, v4
	v_sub_u32_e32 v65, v0, v66
	s_and_b64 s[0:1], vcc, s[0:1]
	s_and_saveexec_b64 s[12:13], s[38:39]
	s_xor_b64 s[78:79], exec, s[12:13]
	s_cbranch_execz .LBB0_275
	v_mov_b32_e32 v14, v1
	v_mov_b32_e32 v15, v1
	v_mov_b32_e32 v0, v1
	v_mov_b32_e32 v2, v1
	v_mov_b32_e32 v3, v1
	v_mov_b32_e32 v4, v1
	v_mov_b32_e32 v5, v1
	v_mov_b32_e32 v6, v1
	v_mov_b32_e32 v7, v1
	v_mov_b32_e32 v8, v1
	v_mov_b32_e32 v9, v1
	v_mov_b32_e32 v10, v1
	v_mov_b32_e32 v11, v1
	v_mov_b32_e32 v12, v1
	v_mov_b32_e32 v13, v1
	v_mov_b64_e32 v[30:31], v[14:15]
	v_mov_b64_e32 v[46:47], v[14:15]
	v_mov_b32_e32 v102, 0xf149f2ca
	v_mov_b32_e32 v112, 0
	v_mov_b64_e32 v[28:29], v[12:13]
	v_mov_b64_e32 v[26:27], v[10:11]
	v_mov_b64_e32 v[24:25], v[8:9]
	v_mov_b64_e32 v[22:23], v[6:7]
	v_mov_b64_e32 v[20:21], v[4:5]
	v_mov_b64_e32 v[18:19], v[2:3]
	v_mov_b64_e32 v[16:17], v[0:1]
	v_mov_b64_e32 v[44:45], v[12:13]
	v_mov_b64_e32 v[42:43], v[10:11]
	v_mov_b64_e32 v[40:41], v[8:9]
	v_mov_b64_e32 v[38:39], v[6:7]
	v_mov_b64_e32 v[36:37], v[4:5]
	v_mov_b64_e32 v[34:35], v[2:3]
	v_mov_b64_e32 v[32:33], v[0:1]
	s_and_saveexec_b64 s[80:81], s[0:1]
	s_cbranch_execz .LBB0_274
; #define MFMA32(a, b, c) __builtin_amdgcn_mfma_f32_32x32x16_bf16((a), (b), (c), 0, 0, 0)
; template <int MODE, int NQ, int TS, bool FAST = false> ...
;     ...
;   auto QK = [&](int slot) {
;     const char* kb_ = lds + slot * 16384;
; #pragma unroll
;     for (int nq = 0; nq < NQ; ++nq)
; #pragma unroll
;       for (int r = 0; r < 16; ++r) { s[nq][0][r] = 0.f; s[nq][1][r] = 0.f; }
; #pragma unroll
;     for (int ks = 0; ks < 4; ++ks) {
;       const bf16x8 k0 = *(const bf16x8*)(kb_ + kfo4[ks]), k1 = *(const bf16x8*)(kb_ + kfo4[ks] + 4096);
; #pragma unroll
;       for (int nq = 0; nq < NQ; ++nq) { s[nq][0] = MFMA32(k0, qf[nq][ks], s[nq][0]); s[nq][1] = MFMA32(k1, qf[nq][ks], s[nq][1]); }
;     }
;   };
;   auto SM = [&](int kt) {
; #pragma unroll
;     for (int nq = 0; nq < NQ; ++nq) {
;       f32x16& s0 = s[nq][0]; f32x16& s1 = s[nq][1];
;       float mx = -1e30f;
;       if (MODE == 1) {
;       } else if (MODE == 0 || MODE == 3) {
;         const float* tb = (const float*)(lds + TAB_OFF) + (kt * 64 + 4 * hh - (q0w + 32 * nq + r32) + TAB_ZERO);
; #pragma unroll
;         for (int r = 0; r < 16; ++r) {
;           const float va = fmaf(s0[r], C2, tb[(r & 3) + 8 * (r >> 2)]), vb = fmaf(s1[r], C2, tb[(r & 3) + 8 * (r >> 2) + 32]);
;           s0[r] = va; s1[r] = vb; mx = fmaxf(mx, fmaxf(va, vb));
;         }
;       } else {
;         const float* tb = (const float*)(lds + TAB_OFF) + (wave & 3) * 512 + (kt * 64 + 4 * hh - (q0w + 32 * nq + r32) + 256);
; #pragma unroll
;         for (int r = 0; r < 16; ++r) {
;           const float va = fmaf(s0[r], C2, tb[(r & 3) + 8 * (r >> 2)]), vb = fmaf(s1[r], C2, tb[(r & 3) + 8 * (r >> 2) + 32]);
;           s0[r] = va; s1[r] = vb; mx = fmaxf(mx, fmaxf(va, vb));
;         }
;       }
;       float mn;
;       if (MODE == 1) {
;         mn = sink2;
;       } else {
;         if (__any(mx > m2[nq] + 8.f)) {
;           mx = fmaxf(mx, __shfl_xor(mx, 32));
;           mn = fmaxf(m2[nq], mx);
;           const float alpha = __builtin_amdgcn_exp2f(m2[nq] - mn);
;           l[nq] *= alpha;
; #pragma unroll
;           for (int r = 0; r < 16; ++r) { o[nq][0][r] *= alpha; o[nq][1][r] *= alpha; }
;           m2[nq] = mn;
;         }
;         mn = m2[nq];
	ds_read_b128 v[2:5], v111
	ds_read_b128 v[18:21], v111 offset:4096
	ds_read_b128 v[34:37], v110
	ds_read_b128 v[38:41], v110 offset:4096
	v_lshlrev_b32_e32 v0, 2, v65
	v_lshl_add_u32 v50, s7, 2, v0
	s_waitcnt lgkmcnt(0)
	v_mfma_f32_32x32x16_bf16 v[2:17], v[2:5], v[80:83], 0
	v_mov_b32_e32 v102, 0xf149f2ca
	v_mfma_f32_32x32x16_bf16 v[18:33], v[18:21], v[80:83], 0
	v_mfma_f32_32x32x16_bf16 v[2:17], v[34:37], v[84:87], v[2:17]
	v_mfma_f32_32x32x16_bf16 v[18:33], v[38:41], v[84:87], v[18:33]
	ds_read_b128 v[34:37], v109
	ds_read_b128 v[38:41], v109 offset:4096
	s_waitcnt lgkmcnt(1)
	v_mfma_f32_32x32x16_bf16 v[2:17], v[34:37], v[88:91], v[2:17]
	s_waitcnt lgkmcnt(0)
	v_mfma_f32_32x32x16_bf16 v[18:33], v[38:41], v[88:91], v[18:33]
	ds_read_b128 v[34:37], v97
	ds_read_b128 v[38:41], v97 offset:4096
	s_waitcnt lgkmcnt(1)
	v_mfma_f32_32x32x16_bf16 v[2:17], v[34:37], v[92:95], v[2:17]
	v_add_u32_e32 v148, 0x18500, v50
	ds_read2_b32 v[116:117], v148 offset0:0 offset1:1
	ds_read2_b32 v[118:119], v148 offset0:32 offset1:33
	ds_read2_b32 v[120:121], v148 offset0:2 offset1:3
	ds_read2_b32 v[122:123], v148 offset0:34 offset1:35
	ds_read2_b32 v[124:125], v148 offset0:8 offset1:9
	ds_read2_b32 v[126:127], v148 offset0:40 offset1:41
	ds_read2_b32 v[128:129], v148 offset0:10 offset1:11
	ds_read2_b32 v[130:131], v148 offset0:42 offset1:43
	ds_read2_b32 v[132:133], v148 offset0:16 offset1:17
	ds_read2_b32 v[134:135], v148 offset0:48 offset1:49
	ds_read2_b32 v[136:137], v148 offset0:18 offset1:19
	ds_read2_b32 v[138:139], v148 offset0:50 offset1:51
	ds_read2_b32 v[140:141], v148 offset0:24 offset1:25
	ds_read2_b32 v[142:143], v148 offset0:56 offset1:57
	ds_read2_b32 v[144:145], v148 offset0:26 offset1:27
	ds_read2_b32 v[146:147], v148 offset0:58 offset1:59
	s_waitcnt lgkmcnt(15)
	v_mfma_f32_32x32x16_bf16 v[18:33], v[38:41], v[92:95], v[18:33]
	s_waitcnt lgkmcnt(0)
	s_nop 9
	v_fmamk_f32 v0, v2, 0x3e38aa3b, v116
	v_fmamk_f32 v35, v3, 0x3e38aa3b, v117
	s_waitcnt lgkmcnt(0)
	v_fmamk_f32 v34, v18, 0x3e38aa3b, v118
	v_fmamk_f32 v37, v19, 0x3e38aa3b, v119
	v_max_f32_e32 v2, v0, v34
	v_max_f32_e32 v3, v35, v37
	v_max3_f32 v18, v2, v102, v3
	s_waitcnt lgkmcnt(0)
	v_fmamk_f32 v2, v4, 0x3e38aa3b, v120
	v_fmamk_f32 v3, v5, 0x3e38aa3b, v121
	s_waitcnt lgkmcnt(0)
	v_fmamk_f32 v38, v20, 0x3e38aa3b, v122
	v_fmamk_f32 v39, v21, 0x3e38aa3b, v123
	v_max_f32_e32 v4, v2, v38
	v_max_f32_e32 v5, v3, v39
	v_max3_f32 v18, v18, v4, v5
	s_waitcnt lgkmcnt(0)
	v_fmamk_f32 v4, v6, 0x3e38aa3b, v124
	v_fmamk_f32 v5, v7, 0x3e38aa3b, v125
	s_waitcnt lgkmcnt(0)
	v_fmamk_f32 v36, v22, 0x3e38aa3b, v126
	v_fmamk_f32 v41, v23, 0x3e38aa3b, v127
	v_max_f32_e32 v6, v4, v36
	v_max_f32_e32 v7, v5, v41
	v_max3_f32 v18, v18, v6, v7
	s_waitcnt lgkmcnt(0)
	v_fmamk_f32 v6, v8, 0x3e38aa3b, v128
	v_fmamk_f32 v7, v9, 0x3e38aa3b, v129
	s_waitcnt lgkmcnt(0)
	v_fmamk_f32 v42, v24, 0x3e38aa3b, v130
	v_fmamk_f32 v43, v25, 0x3e38aa3b, v131
	v_max_f32_e32 v8, v6, v42
	v_max_f32_e32 v9, v7, v43
	v_max3_f32 v18, v18, v8, v9
	s_waitcnt lgkmcnt(0)
	v_fmamk_f32 v8, v10, 0x3e38aa3b, v132
	v_fmamk_f32 v9, v11, 0x3e38aa3b, v133
	s_waitcnt lgkmcnt(0)
	v_fmamk_f32 v40, v26, 0x3e38aa3b, v134
	v_fmamk_f32 v45, v27, 0x3e38aa3b, v135
	v_max_f32_e32 v10, v8, v40
	v_max_f32_e32 v11, v9, v45
	v_max3_f32 v18, v18, v10, v11
	s_waitcnt lgkmcnt(0)
	v_fmamk_f32 v10, v12, 0x3e38aa3b, v136
	v_fmamk_f32 v11, v13, 0x3e38aa3b, v137
	s_waitcnt lgkmcnt(0)
	v_fmamk_f32 v46, v28, 0x3e38aa3b, v138
	v_fmamk_f32 v47, v29, 0x3e38aa3b, v139
	v_max_f32_e32 v12, v10, v46
	v_max_f32_e32 v13, v11, v47
	v_max3_f32 v18, v18, v12, v13
	s_waitcnt lgkmcnt(0)
	v_fmamk_f32 v12, v14, 0x3e38aa3b, v140
	v_fmamk_f32 v13, v15, 0x3e38aa3b, v141
	s_waitcnt lgkmcnt(0)
	v_fmamk_f32 v44, v30, 0x3e38aa3b, v142
	v_fmamk_f32 v49, v31, 0x3e38aa3b, v143
	v_max_f32_e32 v14, v12, v44
	v_max_f32_e32 v15, v13, v49
	v_max3_f32 v18, v18, v14, v15
	s_waitcnt lgkmcnt(0)
	v_fmamk_f32 v14, v16, 0x3e38aa3b, v144
	v_fmamk_f32 v15, v17, 0x3e38aa3b, v145
	s_waitcnt lgkmcnt(0)
	v_fmamk_f32 v32, v32, 0x3e38aa3b, v146
	v_fmamk_f32 v51, v33, 0x3e38aa3b, v147
	v_max_f32_e32 v16, v14, v32
	v_max_f32_e32 v17, v15, v51
	v_max3_f32 v16, v18, v16, v17
	v_cmp_gt_f32_e32 vcc, v16, v102
	s_cbranch_vccz .LBB0_272
	v_xor_b32_e32 v17, 32, v223
	v_cmp_lt_i32_e32 vcc, v17, v225
	s_nop 1
	v_cndmask_b32_e32 v17, v223, v17, vcc
	v_lshlrev_b32_e32 v17, 2, v17
	ds_bpermute_b32 v17, v17, v16
	s_waitcnt lgkmcnt(0)
	v_max3_f32 v102, v16, v17, s25
	v_sub_f32_e32 v16, 0xf149f2ca, v102
	v_exp_f32_e32 v16, v16
	s_nop 0
	v_mul_f32_e32 v16, 0, v16
	s_branch .LBB0_273

; #define MFMA32(a, b, c) __builtin_amdgcn_mfma_f32_32x32x16_bf16((a), (b), (c), 0, 0, 0)
; template <int MODE, int NQ, int TS, bool FAST = false> ...
;     ...
;   auto QK = [&](int slot) {
;     const char* kb_ = lds + slot * 16384;
; #pragma unroll
;     for (int nq = 0; nq < NQ; ++nq)
; #pragma unroll
;       for (int r = 0; r < 16; ++r) { s[nq][0][r] = 0.f; s[nq][1][r] = 0.f; }
; #pragma unroll
;     for (int ks = 0; ks < 4; ++ks) {
;       const bf16x8 k0 = *(const bf16x8*)(kb_ + kfo4[ks]), k1 = *(const bf16x8*)(kb_ + kfo4[ks] + 4096);
; #pragma unroll
;       for (int nq = 0; nq < NQ; ++nq) { s[nq][0] = MFMA32(k0, qf[nq][ks], s[nq][0]); s[nq][1] = MFMA32(k1, qf[nq][ks], s[nq][1]); }
;     }
;   };
;   auto SM = [&](int kt) {
; #pragma unroll
;     for (int nq = 0; nq < NQ; ++nq) {
;       f32x16& s0 = s[nq][0]; f32x16& s1 = s[nq][1];
;       float mx = -1e30f;
;       if (MODE == 1) {
;       } else if (MODE == 0 || MODE == 3) {
;         const float* tb = (const float*)(lds + TAB_OFF) + (kt * 64 + 4 * hh - (q0w + 32 * nq + r32) + TAB_ZERO);
; #pragma unroll
;         for (int r = 0; r < 16; ++r) {
;           const float va = fmaf(s0[r], C2, tb[(r & 3) + 8 * (r >> 2)]), vb = fmaf(s1[r], C2, tb[(r & 3) + 8 * (r >> 2) + 32]);
;           s0[r] = va; s1[r] = vb; mx = fmaxf(mx, fmaxf(va, vb));
;         }
;       } else {
;         const float* tb = (const float*)(lds + TAB_OFF) + (wave & 3) * 512 + (kt * 64 + 4 * hh - (q0w + 32 * nq + r32) + 256);
; #pragma unroll
;         for (int r = 0; r < 16; ++r) {
;           const float va = fmaf(s0[r], C2, tb[(r & 3) + 8 * (r >> 2)]), vb = fmaf(s1[r], C2, tb[(r & 3) + 8 * (r >> 2) + 32]);
;           s0[r] = va; s1[r] = vb; mx = fmaxf(mx, fmaxf(va, vb));
;         }
;       }
;       float mn;
;       if (MODE == 1) {
;         mn = sink2;
;       } else {
;         if (__any(mx > m2[nq] + 8.f)) {
;           mx = fmaxf(mx, __shfl_xor(mx, 32));
;           mn = fmaxf(m2[nq], mx);
;           const float alpha = __builtin_amdgcn_exp2f(m2[nq] - mn);
;           l[nq] *= alpha;
; #pragma unroll
;           for (int r = 0; r < 16; ++r) { o[nq][0][r] *= alpha; o[nq][1][r] *= alpha; }
;           m2[nq] = mn;
;         }
;         mn = m2[nq];
.LBB0_275:
	s_andn2_saveexec_b64 s[28:29], s[78:79]
	s_cbranch_execz .LBB0_282
	v_mov_b32_e32 v14, v1
	v_mov_b32_e32 v15, v1
	v_mov_b32_e32 v0, v1
	v_mov_b32_e32 v2, v1
	v_mov_b32_e32 v3, v1
	v_mov_b32_e32 v4, v1
	v_mov_b32_e32 v5, v1
	v_mov_b32_e32 v6, v1
	v_mov_b32_e32 v7, v1
	v_mov_b32_e32 v8, v1
	v_mov_b32_e32 v9, v1
	v_mov_b32_e32 v10, v1
	v_mov_b32_e32 v11, v1
	v_mov_b32_e32 v12, v1
	v_mov_b32_e32 v13, v1
	v_mov_b64_e32 v[46:47], v[14:15]
	v_mov_b32_e32 v102, 0xf149f2ca
	v_mov_b32_e32 v112, 0
	v_mov_b64_e32 v[44:45], v[12:13]
	v_mov_b64_e32 v[42:43], v[10:11]
	v_mov_b64_e32 v[40:41], v[8:9]
	v_mov_b64_e32 v[38:39], v[6:7]
	v_mov_b64_e32 v[36:37], v[4:5]
	v_mov_b64_e32 v[34:35], v[2:3]
	v_mov_b64_e32 v[32:33], v[0:1]
	s_and_saveexec_b64 s[30:31], s[0:1]
	s_cbranch_execz .LBB0_281
	ds_read_b128 v[2:5], v111
	ds_read_b128 v[18:21], v111 offset:4096
	ds_read_b128 v[34:37], v110
	ds_read_b128 v[38:41], v110 offset:4096
	v_lshlrev_b32_e32 v0, 2, v65
	v_mov_b32_e32 v102, 0xf149f2ca
	s_waitcnt lgkmcnt(0)
	v_mfma_f32_32x32x16_bf16 v[2:17], v[2:5], v[80:83], 0
	v_mfma_f32_32x32x16_bf16 v[18:33], v[18:21], v[80:83], 0
	v_mfma_f32_32x32x16_bf16 v[2:17], v[34:37], v[84:87], v[2:17]
	v_mfma_f32_32x32x16_bf16 v[18:33], v[38:41], v[84:87], v[18:33]
	ds_read_b128 v[34:37], v109
	ds_read_b128 v[38:41], v109 offset:4096
	s_waitcnt lgkmcnt(1)
	v_mfma_f32_32x32x16_bf16 v[2:17], v[34:37], v[88:91], v[2:17]
	s_waitcnt lgkmcnt(0)
	v_mfma_f32_32x32x16_bf16 v[18:33], v[38:41], v[88:91], v[18:33]
	ds_read_b128 v[34:37], v97
	ds_read_b128 v[38:41], v97 offset:4096
	s_waitcnt lgkmcnt(1)
	v_mfma_f32_32x32x16_bf16 v[2:17], v[34:37], v[92:95], v[2:17]
	v_lshl_add_u32 v34, s7, 2, v0
	v_add_u32_e32 v148, 0x18500, v34
	ds_read2_b32 v[116:117], v148 offset0:0 offset1:1
	ds_read2_b32 v[118:119], v148 offset0:32 offset1:33
	ds_read2_b32 v[120:121], v148 offset0:2 offset1:3
	ds_read2_b32 v[122:123], v148 offset0:34 offset1:35
	ds_read2_b32 v[124:125], v148 offset0:8 offset1:9
	ds_read2_b32 v[126:127], v148 offset0:40 offset1:41
	ds_read2_b32 v[128:129], v148 offset0:10 offset1:11
	ds_read2_b32 v[130:131], v148 offset0:42 offset1:43
	ds_read2_b32 v[132:133], v148 offset0:16 offset1:17
	ds_read2_b32 v[134:135], v148 offset0:48 offset1:49
	ds_read2_b32 v[136:137], v148 offset0:18 offset1:19
	ds_read2_b32 v[138:139], v148 offset0:50 offset1:51
	ds_read2_b32 v[140:141], v148 offset0:24 offset1:25
	ds_read2_b32 v[142:143], v148 offset0:56 offset1:57
	ds_read2_b32 v[144:145], v148 offset0:26 offset1:27
	ds_read2_b32 v[146:147], v148 offset0:58 offset1:59
	s_waitcnt lgkmcnt(15)
	v_mfma_f32_32x32x16_bf16 v[18:33], v[38:41], v[92:95], v[18:33]
	s_waitcnt lgkmcnt(0)
	s_nop 8
	v_fmamk_f32 v0, v2, 0x3e38aa3b, v116
	v_fmamk_f32 v49, v3, 0x3e38aa3b, v117
	s_waitcnt lgkmcnt(0)
	v_fmamk_f32 v48, v18, 0x3e38aa3b, v118
	v_fmamk_f32 v51, v19, 0x3e38aa3b, v119
	v_max_f32_e32 v2, v0, v48
	v_max_f32_e32 v3, v49, v51
	v_max3_f32 v35, v2, v102, v3
	s_waitcnt lgkmcnt(0)
	v_fmamk_f32 v2, v4, 0x3e38aa3b, v120
	v_fmamk_f32 v3, v5, 0x3e38aa3b, v121
	s_waitcnt lgkmcnt(0)
	v_fmamk_f32 v18, v20, 0x3e38aa3b, v122
	v_fmamk_f32 v19, v21, 0x3e38aa3b, v123
	v_max_f32_e32 v4, v2, v18
	v_max_f32_e32 v5, v3, v19
	v_max3_f32 v35, v35, v4, v5
	s_waitcnt lgkmcnt(0)
	v_fmamk_f32 v4, v6, 0x3e38aa3b, v124
	v_fmamk_f32 v5, v7, 0x3e38aa3b, v125
	s_waitcnt lgkmcnt(0)
	v_fmamk_f32 v20, v22, 0x3e38aa3b, v126
	v_fmamk_f32 v21, v23, 0x3e38aa3b, v127
	v_max_f32_e32 v6, v4, v20
	v_max_f32_e32 v7, v5, v21
	v_max3_f32 v35, v35, v6, v7
	s_waitcnt lgkmcnt(0)
	v_fmamk_f32 v6, v8, 0x3e38aa3b, v128
	v_fmamk_f32 v7, v9, 0x3e38aa3b, v129
	s_waitcnt lgkmcnt(0)
	v_fmamk_f32 v22, v24, 0x3e38aa3b, v130
	v_fmamk_f32 v23, v25, 0x3e38aa3b, v131
	v_max_f32_e32 v8, v6, v22
	v_max_f32_e32 v9, v7, v23
	v_max3_f32 v35, v35, v8, v9
	s_waitcnt lgkmcnt(0)
	v_fmamk_f32 v8, v10, 0x3e38aa3b, v132
	v_fmamk_f32 v9, v11, 0x3e38aa3b, v133
	s_waitcnt lgkmcnt(0)
	v_fmamk_f32 v24, v26, 0x3e38aa3b, v134
	v_fmamk_f32 v25, v27, 0x3e38aa3b, v135
	v_max_f32_e32 v10, v8, v24
	v_max_f32_e32 v11, v9, v25
	v_max3_f32 v35, v35, v10, v11
	s_waitcnt lgkmcnt(0)
	v_fmamk_f32 v10, v12, 0x3e38aa3b, v136
	v_fmamk_f32 v11, v13, 0x3e38aa3b, v137
	s_waitcnt lgkmcnt(0)
	v_fmamk_f32 v26, v28, 0x3e38aa3b, v138
	v_fmamk_f32 v27, v29, 0x3e38aa3b, v139
	v_max_f32_e32 v12, v10, v26
	v_max_f32_e32 v13, v11, v27
	v_max3_f32 v35, v35, v12, v13
	s_waitcnt lgkmcnt(0)
	v_fmamk_f32 v12, v14, 0x3e38aa3b, v140
	v_fmamk_f32 v13, v15, 0x3e38aa3b, v141
	s_waitcnt lgkmcnt(0)
	v_fmamk_f32 v28, v30, 0x3e38aa3b, v142
	v_fmamk_f32 v29, v31, 0x3e38aa3b, v143
	v_max_f32_e32 v14, v12, v28
	v_max_f32_e32 v15, v13, v29
	v_max3_f32 v35, v35, v14, v15
	s_waitcnt lgkmcnt(0)
	v_fmamk_f32 v14, v16, 0x3e38aa3b, v144
	v_fmamk_f32 v15, v17, 0x3e38aa3b, v145
	s_waitcnt lgkmcnt(0)
	v_fmamk_f32 v16, v32, 0x3e38aa3b, v146
	v_fmamk_f32 v31, v33, 0x3e38aa3b, v147
	v_max_f32_e32 v30, v14, v16
	v_max_f32_e32 v17, v15, v31
	v_max3_f32 v17, v35, v30, v17
	v_cmp_gt_f32_e32 vcc, v17, v102
	s_cbranch_vccz .LBB0_279
	v_xor_b32_e32 v30, 32, v223
	v_cmp_lt_i32_e32 vcc, v30, v225
	s_nop 1
	v_cndmask_b32_e32 v30, v223, v30, vcc
	v_lshlrev_b32_e32 v30, 2, v30
	ds_bpermute_b32 v30, v30, v17
	s_waitcnt lgkmcnt(0)
	v_max3_f32 v102, v17, v30, s25
	v_sub_f32_e32 v17, 0xf149f2ca, v102
	v_exp_f32_e32 v17, v17
	s_nop 0
	v_mul_f32_e32 v32, 0, v17
	v_mov_b32_e32 v33, v32
	v_mov_b32_e32 v34, v32
	v_mov_b32_e32 v35, v32
	v_mov_b32_e32 v36, v32
	v_mov_b32_e32 v37, v32
	v_mov_b32_e32 v38, v32
	v_mov_b32_e32 v39, v32
	v_mov_b32_e32 v40, v32
	v_mov_b32_e32 v41, v32
	v_mov_b32_e32 v42, v32
	v_mov_b32_e32 v43, v32
	v_mov_b32_e32 v44, v32
	v_mov_b32_e32 v45, v32
	v_mov_b32_e32 v46, v32
	v_mov_b32_e32 v47, v32
	v_mov_b32_e32 v17, v32
	s_branch .LBB0_280
